# weight-transpose items with a row scale: the 8 scale loads issued as one batch instead of 4 serialized pairs
# baseline (speedup 1.0000x reference)
.LBB0_80:
	s_cmp_lg_u64 s[18:19], 0
	s_cselect_b64 s[26:27], -1, 0
	s_cmp_eq_u64 s[18:19], 0
	s_cbranch_scc1 .LBB0_108
	v_add_u32_e32 v86, s16, v68
	v_ashrrev_i32_e32 v87, 31, v86
	v_lshl_add_u64 v[86:87], v[86:87], 2, s[18:19]
	global_load_dword v200, v[86:87], off offset:64
	global_load_dword v201, v[86:87], off offset:96
	global_load_dword v202, v[86:87], off offset:128
	global_load_dword v203, v[86:87], off offset:160
	global_load_dword v204, v[86:87], off offset:192
	global_load_dword v205, v[86:87], off offset:224
	global_load_dword v75, v[86:87], off
	global_load_dword v76, v[86:87], off offset:32
	s_waitcnt vmcnt(1)
	v_mul_f32_e32 v86, s34, v75
	s_waitcnt vmcnt(0)
	v_mul_f32_e32 v76, s34, v76
	v_pk_mul_f32 v[88:89], v[4:5], v[86:87] op_sel_hi:[1,0]
	v_pk_mul_f32 v[86:87], v[6:7], v[86:87] op_sel_hi:[1,0]
	ds_write2_b32 v82, v88, v89 offset1:1
	ds_write2_b32 v82, v86, v87 offset0:2 offset1:3
	s_cbranch_execnz .LBB0_83

.LBB0_83:
	s_waitcnt vmcnt(6)
	v_pk_mul_f32 v[86:87], v[8:9], v[76:77] op_sel_hi:[1,0]
	v_cndmask_b32_e64 v75, 0, 1, s[26:27]
	ds_write2_b32 v83, v86, v87 offset1:1
	v_pk_mul_f32 v[86:87], v[10:11], v[76:77] op_sel_hi:[1,0]
	v_cmp_ne_u32_e64 s[6:7], 1, v75
	s_andn2_b64 vcc, exec, s[26:27]
	ds_write2_b32 v83, v86, v87 offset0:2 offset1:3
	s_cbranch_vccnz .LBB0_109
	s_ashr_i32 s17, s16, 31
	v_lshl_add_u64 v[86:87], s[16:17], 0, v[68:69]
	v_lshl_add_u64 v[86:87], v[86:87], 2, s[18:19]
	s_waitcnt vmcnt(1)
	v_mul_f32_e32 v86, s34, v200
	s_waitcnt vmcnt(0)
	v_mul_f32_e32 v76, s34, v201
	v_pk_mul_f32 v[88:89], v[12:13], v[86:87] op_sel_hi:[1,0]
	v_pk_mul_f32 v[86:87], v[14:15], v[86:87] op_sel_hi:[1,0]
	ds_write2_b32 v84, v88, v89 offset1:1
	ds_write2_b32 v84, v86, v87 offset0:2 offset1:3
	s_cbranch_execnz .LBB0_86

.LBB0_86:
	s_waitcnt vmcnt(4)
	v_pk_mul_f32 v[86:87], v[16:17], v[76:77] op_sel_hi:[1,0]
	v_add_u32_e32 v90, 0x420, v84
	ds_write2_b32 v90, v86, v87 offset1:1
	v_pk_mul_f32 v[86:87], v[18:19], v[76:77] op_sel_hi:[1,0]
	v_add_u32_e32 v89, 0x428, v84
	ds_write2_b32 v89, v86, v87 offset1:1
	s_and_b64 vcc, exec, s[6:7]
	v_add_u32_e32 v85, 0x840, v84
	v_add_u32_e32 v86, 0x848, v84
	s_cbranch_vccnz .LBB0_110
	s_ashr_i32 s17, s16, 31
	v_lshl_add_u64 v[92:93], s[16:17], 0, v[68:69]
	v_lshl_add_u64 v[92:93], v[92:93], 2, s[18:19]
	s_waitcnt vmcnt(1)
	v_mul_f32_e32 v88, s34, v202
	s_waitcnt vmcnt(0)
	v_mul_f32_e32 v76, s34, v203
	v_pk_mul_f32 v[92:93], v[20:21], v[88:89] op_sel_hi:[1,0]
	v_pk_mul_f32 v[94:95], v[22:23], v[88:89] op_sel_hi:[1,0]
	ds_write2_b32 v85, v92, v93 offset1:1
	ds_write2_b32 v86, v94, v95 offset1:1
	s_cbranch_execnz .LBB0_89

.LBB0_89:
	s_waitcnt vmcnt(2)
	v_pk_mul_f32 v[94:95], v[24:25], v[76:77] op_sel_hi:[1,0]
	v_add_u32_e32 v92, 0xc60, v84
	ds_write2_b32 v92, v94, v95 offset1:1
	v_pk_mul_f32 v[94:95], v[26:27], v[76:77] op_sel_hi:[1,0]
	v_add_u32_e32 v91, 0xc68, v84
	s_and_b64 vcc, exec, s[6:7]
	v_add_u32_e32 v87, 0x1080, v84
	v_add_u32_e32 v88, 0x1088, v84
	ds_write2_b32 v91, v94, v95 offset1:1
	s_cbranch_vccnz .LBB0_111
	s_ashr_i32 s17, s16, 31
	v_lshl_add_u64 v[94:95], s[16:17], 0, v[68:69]
	v_lshl_add_u64 v[94:95], v[94:95], 2, s[18:19]
	s_waitcnt vmcnt(1)
	v_mul_f32_e32 v94, s34, v204
	s_waitcnt vmcnt(0)
	v_mul_f32_e32 v76, s34, v205
	v_pk_mul_f32 v[96:97], v[28:29], v[94:95] op_sel_hi:[1,0]
	v_pk_mul_f32 v[94:95], v[30:31], v[94:95] op_sel_hi:[1,0]
	ds_write2_b32 v87, v96, v97 offset1:1
	ds_write2_b32 v88, v94, v95 offset1:1
	s_cbranch_execnz .LBB0_92

.LBB0_126:
	s_cmp_lg_u64 s[82:83], 0
	s_cselect_b64 s[92:93], -1, 0
	s_cmp_eq_u64 s[82:83], 0
	s_cbranch_scc1 .LBB0_137
	v_add_u32_e32 v74, s80, v68
	v_ashrrev_i32_e32 v75, 31, v74
	v_lshl_add_u64 v[74:75], v[74:75], 2, s[82:83]
	global_load_dword v200, v[74:75], off offset:64
	global_load_dword v201, v[74:75], off offset:96
	global_load_dword v202, v[74:75], off offset:128
	global_load_dword v203, v[74:75], off offset:160
	global_load_dword v204, v[74:75], off offset:192
	global_load_dword v205, v[74:75], off offset:224
	global_load_dword v94, v[74:75], off
	s_nop 0
	global_load_dword v74, v[74:75], off offset:32
	s_waitcnt vmcnt(1)
	v_mul_f32_e32 v94, s35, v94
	s_waitcnt vmcnt(0)
	v_mul_f32_e32 v74, s35, v74
	v_pk_mul_f32 v[96:97], v[36:37], v[94:95] op_sel_hi:[1,0]
	v_pk_mul_f32 v[94:95], v[38:39], v[94:95] op_sel_hi:[1,0]
	ds_write2_b32 v82, v96, v97 offset1:1
	ds_write2_b32 v82, v94, v95 offset0:2 offset1:3
	s_cbranch_execnz .LBB0_129

.LBB0_129:
	v_pk_mul_f32 v[94:95], v[40:41], v[74:75] op_sel_hi:[1,0]
	ds_write2_b32 v83, v94, v95 offset1:1
	v_cndmask_b32_e64 v94, 0, 1, s[92:93]
	v_pk_mul_f32 v[74:75], v[42:43], v[74:75] op_sel_hi:[1,0]
	v_cmp_ne_u32_e64 s[6:7], 1, v94
	s_andn2_b64 vcc, exec, s[92:93]
	ds_write2_b32 v83, v74, v75 offset0:2 offset1:3
	s_cbranch_vccnz .LBB0_138
	s_ashr_i32 s81, s80, 31
	v_lshl_add_u64 v[74:75], s[80:81], 0, v[68:69]
	v_lshl_add_u64 v[74:75], v[74:75], 2, s[82:83]
	s_waitcnt vmcnt(1)
	v_mul_f32_e32 v94, s35, v200
	s_waitcnt vmcnt(0)
	v_mul_f32_e32 v74, s35, v201
	v_pk_mul_f32 v[96:97], v[48:49], v[94:95] op_sel_hi:[1,0]
	v_pk_mul_f32 v[94:95], v[50:51], v[94:95] op_sel_hi:[1,0]
	ds_write2_b32 v84, v96, v97 offset1:1
	ds_write2_b32 v84, v94, v95 offset0:2 offset1:3
	s_cbranch_execnz .LBB0_132

.LBB0_132:
	v_pk_mul_f32 v[94:95], v[44:45], v[74:75] op_sel_hi:[1,0]
	v_pk_mul_f32 v[74:75], v[46:47], v[74:75] op_sel_hi:[1,0]
	s_and_b64 vcc, exec, s[6:7]
	ds_write2_b32 v90, v94, v95 offset1:1
	ds_write2_b32 v89, v74, v75 offset1:1
	s_cbranch_vccnz .LBB0_139
	s_ashr_i32 s81, s80, 31
	v_lshl_add_u64 v[74:75], s[80:81], 0, v[68:69]
	v_lshl_add_u64 v[74:75], v[74:75], 2, s[82:83]
	s_waitcnt vmcnt(1)
	v_mul_f32_e32 v90, s35, v202
	s_waitcnt vmcnt(0)
	v_mul_f32_e32 v74, s35, v203
	v_pk_mul_f32 v[94:95], v[56:57], v[90:91] op_sel_hi:[1,0]
	v_pk_mul_f32 v[96:97], v[58:59], v[90:91] op_sel_hi:[1,0]
	ds_write2_b32 v85, v94, v95 offset1:1
	ds_write2_b32 v86, v96, v97 offset1:1
	s_cbranch_execnz .LBB0_135

.LBB0_135:
	v_pk_mul_f32 v[94:95], v[52:53], v[74:75] op_sel_hi:[1,0]
	v_pk_mul_f32 v[74:75], v[54:55], v[74:75] op_sel_hi:[1,0]
	s_and_b64 vcc, exec, s[6:7]
	ds_write2_b32 v92, v94, v95 offset1:1
	ds_write2_b32 v91, v74, v75 offset1:1
	s_cbranch_vccnz .LBB0_140
	s_ashr_i32 s81, s80, 31
	v_lshl_add_u64 v[74:75], s[80:81], 0, v[68:69]
	v_lshl_add_u64 v[74:75], v[74:75], 2, s[82:83]
	s_waitcnt vmcnt(1)
	v_mul_f32_e32 v86, s35, v204
	s_waitcnt vmcnt(0)
	v_mul_f32_e32 v74, s35, v205
	v_pk_mul_f32 v[90:91], v[64:65], v[86:87] op_sel_hi:[1,0]
	v_pk_mul_f32 v[94:95], v[66:67], v[86:87] op_sel_hi:[1,0]
	ds_write2_b32 v87, v90, v91 offset1:1
	ds_write2_b32 v88, v94, v95 offset1:1
	s_cbranch_execnz .LBB0_49
	s_branch .LBB0_48

.LBB0_307:
	s_cmp_lg_u64 s[16:17], 0
	s_cselect_b64 s[26:27], -1, 0
	s_cmp_eq_u64 s[16:17], 0
	s_cbranch_scc1 .LBB0_335
	v_add_u32_e32 v84, s14, v68
	v_ashrrev_i32_e32 v85, 31, v84
	v_lshl_add_u64 v[84:85], v[84:85], 2, s[16:17]
	global_load_dword v200, v[84:85], off offset:64
	global_load_dword v201, v[84:85], off offset:96
	global_load_dword v202, v[84:85], off offset:128
	global_load_dword v203, v[84:85], off offset:160
	global_load_dword v204, v[84:85], off offset:192
	global_load_dword v205, v[84:85], off offset:224
	global_load_dword v73, v[84:85], off
	global_load_dword v74, v[84:85], off offset:32
	s_waitcnt vmcnt(1)
	v_mul_f32_e32 v84, s34, v73
	s_waitcnt vmcnt(0)
	v_mul_f32_e32 v74, s34, v74
	v_pk_mul_f32 v[86:87], v[4:5], v[84:85] op_sel_hi:[1,0]
	v_pk_mul_f32 v[84:85], v[6:7], v[84:85] op_sel_hi:[1,0]
	ds_write2_b32 v81, v86, v87 offset1:1
	ds_write2_b32 v81, v84, v85 offset0:2 offset1:3
	s_cbranch_execnz .LBB0_310

.LBB0_310:
	s_waitcnt vmcnt(6)
	v_pk_mul_f32 v[84:85], v[8:9], v[74:75] op_sel_hi:[1,0]
	v_cndmask_b32_e64 v73, 0, 1, s[26:27]
	ds_write2_b32 v82, v84, v85 offset1:1
	v_pk_mul_f32 v[84:85], v[10:11], v[74:75] op_sel_hi:[1,0]
	v_cmp_ne_u32_e64 s[8:9], 1, v73
	s_andn2_b64 vcc, exec, s[26:27]
	ds_write2_b32 v82, v84, v85 offset0:2 offset1:3
	s_cbranch_vccnz .LBB0_336
	s_ashr_i32 s15, s14, 31
	v_lshl_add_u64 v[84:85], s[14:15], 0, v[68:69]
	v_lshl_add_u64 v[84:85], v[84:85], 2, s[16:17]
	s_waitcnt vmcnt(1)
	v_mul_f32_e32 v84, s34, v200
	s_waitcnt vmcnt(0)
	v_mul_f32_e32 v74, s34, v201
	v_pk_mul_f32 v[86:87], v[12:13], v[84:85] op_sel_hi:[1,0]
	v_pk_mul_f32 v[84:85], v[14:15], v[84:85] op_sel_hi:[1,0]
	ds_write2_b32 v83, v86, v87 offset1:1
	ds_write2_b32 v83, v84, v85 offset0:2 offset1:3
	s_cbranch_execnz .LBB0_313

.LBB0_313:
	s_waitcnt vmcnt(4)
	v_pk_mul_f32 v[84:85], v[16:17], v[74:75] op_sel_hi:[1,0]
	v_add_u32_e32 v89, 0x420, v83
	ds_write2_b32 v89, v84, v85 offset1:1
	v_pk_mul_f32 v[84:85], v[18:19], v[74:75] op_sel_hi:[1,0]
	v_add_u32_e32 v88, 0x428, v83
	ds_write2_b32 v88, v84, v85 offset1:1
	s_and_b64 vcc, exec, s[8:9]
	v_add_u32_e32 v84, 0x840, v83
	v_add_u32_e32 v85, 0x848, v83
	s_cbranch_vccnz .LBB0_337
	s_ashr_i32 s15, s14, 31
	v_lshl_add_u64 v[86:87], s[14:15], 0, v[68:69]
	v_lshl_add_u64 v[86:87], v[86:87], 2, s[16:17]
	s_waitcnt vmcnt(1)
	v_mul_f32_e32 v86, s34, v202
	s_waitcnt vmcnt(0)
	v_mul_f32_e32 v74, s34, v203
	v_pk_mul_f32 v[90:91], v[20:21], v[86:87] op_sel_hi:[1,0]
	v_pk_mul_f32 v[86:87], v[22:23], v[86:87] op_sel_hi:[1,0]
	ds_write2_b32 v84, v90, v91 offset1:1
	ds_write2_b32 v85, v86, v87 offset1:1
	s_cbranch_execnz .LBB0_316

.LBB0_316:
	s_waitcnt vmcnt(2)
	v_pk_mul_f32 v[86:87], v[24:25], v[74:75] op_sel_hi:[1,0]
	v_add_u32_e32 v91, 0xc60, v83
	ds_write2_b32 v91, v86, v87 offset1:1
	v_pk_mul_f32 v[86:87], v[26:27], v[74:75] op_sel_hi:[1,0]
	v_add_u32_e32 v90, 0xc68, v83
	ds_write2_b32 v90, v86, v87 offset1:1
	s_and_b64 vcc, exec, s[8:9]
	v_add_u32_e32 v86, 0x1080, v83
	v_add_u32_e32 v87, 0x1088, v83
	s_cbranch_vccnz .LBB0_338
	s_ashr_i32 s15, s14, 31
	v_lshl_add_u64 v[92:93], s[14:15], 0, v[68:69]
	v_lshl_add_u64 v[92:93], v[92:93], 2, s[16:17]
	s_waitcnt vmcnt(1)
	v_mul_f32_e32 v92, s34, v204
	s_waitcnt vmcnt(0)
	v_mul_f32_e32 v74, s34, v205
	v_pk_mul_f32 v[94:95], v[28:29], v[92:93] op_sel_hi:[1,0]
	v_pk_mul_f32 v[92:93], v[30:31], v[92:93] op_sel_hi:[1,0]
	ds_write2_b32 v86, v94, v95 offset1:1
	ds_write2_b32 v87, v92, v93 offset1:1
	s_cbranch_execnz .LBB0_319

.LBB0_353:
	s_cmp_lg_u64 s[44:45], 0
	s_cselect_b64 s[26:27], -1, 0
	s_cmp_eq_u64 s[44:45], 0
	s_cbranch_scc1 .LBB0_364
	v_add_u32_e32 v72, s30, v68
	v_ashrrev_i32_e32 v73, 31, v72
	v_lshl_add_u64 v[72:73], v[72:73], 2, s[44:45]
	global_load_dword v200, v[72:73], off offset:64
	global_load_dword v201, v[72:73], off offset:96
	global_load_dword v202, v[72:73], off offset:128
	global_load_dword v203, v[72:73], off offset:160
	global_load_dword v204, v[72:73], off offset:192
	global_load_dword v205, v[72:73], off offset:224
	global_load_dword v93, v[72:73], off
	s_nop 0
	global_load_dword v72, v[72:73], off offset:32
	s_waitcnt vmcnt(1)
	v_mul_f32_e32 v94, s35, v93
	s_waitcnt vmcnt(0)
	v_mul_f32_e32 v72, s35, v72
	v_pk_mul_f32 v[96:97], v[36:37], v[94:95] op_sel_hi:[1,0]
	v_pk_mul_f32 v[94:95], v[38:39], v[94:95] op_sel_hi:[1,0]
	ds_write2_b32 v81, v96, v97 offset1:1
	ds_write2_b32 v81, v94, v95 offset0:2 offset1:3
	s_cbranch_execnz .LBB0_356

.LBB0_356:
	v_cndmask_b32_e64 v93, 0, 1, s[26:27]
	v_pk_mul_f32 v[94:95], v[40:41], v[72:73] op_sel_hi:[1,0]
	v_pk_mul_f32 v[72:73], v[42:43], v[72:73] op_sel_hi:[1,0]
	v_cmp_ne_u32_e64 s[6:7], 1, v93
	s_andn2_b64 vcc, exec, s[26:27]
	ds_write2_b32 v82, v94, v95 offset1:1
	ds_write2_b32 v82, v72, v73 offset0:2 offset1:3
	s_cbranch_vccnz .LBB0_365
	s_ashr_i32 s31, s30, 31
	v_lshl_add_u64 v[72:73], s[30:31], 0, v[68:69]
	v_lshl_add_u64 v[72:73], v[72:73], 2, s[44:45]
	s_waitcnt vmcnt(1)
	v_mul_f32_e32 v94, s35, v200
	s_waitcnt vmcnt(0)
	v_mul_f32_e32 v72, s35, v201
	v_pk_mul_f32 v[96:97], v[48:49], v[94:95] op_sel_hi:[1,0]
	v_pk_mul_f32 v[94:95], v[50:51], v[94:95] op_sel_hi:[1,0]
	ds_write2_b32 v83, v96, v97 offset1:1
	ds_write2_b32 v83, v94, v95 offset0:2 offset1:3
	s_cbranch_execnz .LBB0_359

.LBB0_359:
	v_pk_mul_f32 v[94:95], v[44:45], v[72:73] op_sel_hi:[1,0]
	v_pk_mul_f32 v[72:73], v[46:47], v[72:73] op_sel_hi:[1,0]
	s_and_b64 vcc, exec, s[6:7]
	ds_write2_b32 v89, v94, v95 offset1:1
	ds_write2_b32 v88, v72, v73 offset1:1
	s_cbranch_vccnz .LBB0_366
	s_ashr_i32 s31, s30, 31
	v_lshl_add_u64 v[72:73], s[30:31], 0, v[68:69]
	v_lshl_add_u64 v[72:73], v[72:73], 2, s[44:45]
	s_waitcnt vmcnt(1)
	v_mul_f32_e32 v88, s35, v202
	s_waitcnt vmcnt(0)
	v_mul_f32_e32 v72, s35, v203
	v_pk_mul_f32 v[94:95], v[56:57], v[88:89] op_sel_hi:[1,0]
	v_pk_mul_f32 v[88:89], v[58:59], v[88:89] op_sel_hi:[1,0]
	ds_write2_b32 v84, v94, v95 offset1:1
	ds_write2_b32 v85, v88, v89 offset1:1
	s_cbranch_execnz .LBB0_362

.LBB0_362:
	v_pk_mul_f32 v[84:85], v[52:53], v[72:73] op_sel_hi:[1,0]
	v_pk_mul_f32 v[72:73], v[54:55], v[72:73] op_sel_hi:[1,0]
	s_and_b64 vcc, exec, s[6:7]
	ds_write2_b32 v91, v84, v85 offset1:1
	ds_write2_b32 v90, v72, v73 offset1:1
	s_cbranch_vccnz .LBB0_367
	s_ashr_i32 s31, s30, 31
	v_lshl_add_u64 v[72:73], s[30:31], 0, v[68:69]
	v_lshl_add_u64 v[72:73], v[72:73], 2, s[44:45]
	s_waitcnt vmcnt(1)
	v_mul_f32_e32 v84, s35, v204
	s_waitcnt vmcnt(0)
	v_mul_f32_e32 v72, s35, v205
	v_pk_mul_f32 v[88:89], v[64:65], v[84:85] op_sel_hi:[1,0]
	v_pk_mul_f32 v[84:85], v[66:67], v[84:85] op_sel_hi:[1,0]
	ds_write2_b32 v86, v88, v89 offset1:1
	ds_write2_b32 v87, v84, v85 offset1:1
	s_cbranch_execnz .LBB0_276
	s_branch .LBB0_275
